# v42 + MLA in-loop tiles: same exp/cvt-under-PV-MFMA interleave (fresh temps for the register-reuse chains, counted lgkmcnt waits kept per V fragment)
# speedup vs baseline: 1.0065x; 1.0043x over previous
; __device__ __forceinline__ unsigned cvt_pk_bf16(float lo, float hi) { f32x2 v = {lo, hi}; bf16x2_t b = __builtin_convertvector(v, bf16x2_t); return __builtin_bit_cast(unsigned, b); }
; template <int TY> __device__ __forceinline__ void attn_unit(LAS unsigned char* lds, const AttnArgs& a, int b, int h, int qt, int wave_s) {
;     ...
; #pragma unroll
;         for (int qb = 0; qb < 2; ++qb) {
; #pragma unroll
;             for (int kb = 0; kb < 4; ++kb)
; #pragma unroll
;                 for (int r = 0; r < 4; ++r) s[qb][kb][r] = __builtin_amdgcn_exp2f(s[qb][kb][r]);
; #pragma unroll
;             for (int G = 0; G < 2; ++G) {
;                 u32x4 w; w.x = cvt_pk_bf16(s[qb][2 * G][0], s[qb][2 * G][1]); w.y = cvt_pk_bf16(s[qb][2 * G][2], s[qb][2 * G][3]);
;                 w.z = cvt_pk_bf16(s[qb][2 * G + 1][0], s[qb][2 * G + 1][1]); w.w = cvt_pk_bf16(s[qb][2 * G + 1][2], s[qb][2 * G + 1][3]);
;                 pf[qb][G] = __builtin_bit_cast(bf16x8, w);
;             }
;         }
; #pragma unroll
;         for (int G = 0; G < 2; ++G) {
;             lacc[0] = __builtin_amdgcn_mfma_f32_16x16x32_bf16(ones, pf[0][G], lacc[0], 0, 0, 0);
;             lacc[1] = __builtin_amdgcn_mfma_f32_16x16x32_bf16(ones, pf[1][G], lacc[1], 0, 0, 0);
;         }
; #pragma unroll
;         for (int db = 0; db < 4; ++db)
; #pragma unroll
;             for (int G = 0; G < 2; ++G) {
;                 o[0][db] = __builtin_amdgcn_mfma_f32_16x16x32_bf16(vf[db][G], pf[0][G], o[0][db], 0, 0, 0);
;                 o[1][db] = __builtin_amdgcn_mfma_f32_16x16x32_bf16(vf[db][G], pf[1][G], o[1][db], 0, 0, 0);
;             }
.LBB0_708:
	v_exp_f32_e32 v130, v130
	v_exp_f32_e32 v131, v131
	v_exp_f32_e32 v132, v132
	v_exp_f32_e32 v133, v133
	v_exp_f32_e32 v146, v146
	v_exp_f32_e32 v147, v147
	v_exp_f32_e32 v148, v148
	v_exp_f32_e32 v149, v149
	v_exp_f32_e32 v10, v10
	v_exp_f32_e32 v11, v11
	v_exp_f32_e32 v12, v12
	v_exp_f32_e32 v13, v13
	v_exp_f32_e32 v232, v106
	v_exp_f32_e32 v233, v107
	v_exp_f32_e32 v234, v108
	v_exp_f32_e32 v235, v109
	v_cvt_pk_bf16_f32 v130, v130, v131
	v_cvt_pk_bf16_f32 v131, v132, v133
	v_cvt_pk_bf16_f32 v132, v146, v147
	v_cvt_pk_bf16_f32 v133, v148, v149
	v_cvt_pk_bf16_f32 v10, v10, v11
	v_cvt_pk_bf16_f32 v11, v12, v13
	v_cvt_pk_bf16_f32 v12, v232, v233
	v_cvt_pk_bf16_f32 v13, v234, v235
	v_mfma_f32_16x16x32_bf16 v[2:5], v[54:57], v[130:133], v[2:5]
	v_exp_f32_e32 v126, v126
	v_mfma_f32_16x16x32_bf16 v[6:9], v[54:57], v[10:13], v[6:9]
	v_exp_f32_e32 v127, v127
	s_waitcnt lgkmcnt(13)
	v_mfma_f32_16x16x32_bf16 v[102:105], v[122:125], v[130:133], v[102:105]
	v_exp_f32_e32 v128, v128
	v_mfma_f32_16x16x32_bf16 v[34:37], v[122:125], v[10:13], v[34:37]
	v_exp_f32_e32 v129, v129
	s_waitcnt lgkmcnt(10)
	v_mfma_f32_16x16x32_bf16 v[98:101], v[110:113], v[130:133], v[98:101]
	v_exp_f32_e32 v134, v134
	v_mfma_f32_16x16x32_bf16 v[30:33], v[110:113], v[10:13], v[30:33]
	v_exp_f32_e32 v135, v135
	s_waitcnt lgkmcnt(6)
	v_mfma_f32_16x16x32_bf16 v[94:97], v[142:145], v[130:133], v[94:97]
	v_exp_f32_e32 v136, v136
	v_mfma_f32_16x16x32_bf16 v[26:29], v[142:145], v[10:13], v[26:29]
	v_exp_f32_e32 v137, v137
	s_waitcnt lgkmcnt(2)
	v_mfma_f32_16x16x32_bf16 v[90:93], v[150:153], v[130:133], v[90:93]
	v_cvt_pk_bf16_f32 v106, v126, v127
	v_cvt_pk_bf16_f32 v107, v128, v129
	v_mfma_f32_16x16x32_bf16 v[22:25], v[150:153], v[10:13], v[22:25]
	v_cvt_pk_bf16_f32 v108, v134, v135
	v_cvt_pk_bf16_f32 v109, v136, v137
	v_exp_f32_e32 v236, v14
	v_exp_f32_e32 v237, v15
	v_mfma_f32_16x16x32_bf16 v[6:9], v[54:57], v[106:109], v[6:9]
	v_exp_f32_e32 v16, v16
	v_mfma_f32_16x16x32_bf16 v[34:37], v[118:121], v[106:109], v[34:37]
	v_exp_f32_e32 v17, v17
	v_mfma_f32_16x16x32_bf16 v[30:33], v[114:117], v[106:109], v[30:33]
	v_exp_f32_e32 v154, v154
	v_mfma_f32_16x16x32_bf16 v[26:29], v[138:141], v[106:109], v[26:29]
	v_exp_f32_e32 v155, v155
	s_waitcnt lgkmcnt(0)
	v_mfma_f32_16x16x32_bf16 v[22:25], v[158:161], v[106:109], v[22:25]
	v_exp_f32_e32 v156, v156
	v_exp_f32_e32 v157, v157
	v_cvt_pk_bf16_f32 v14, v154, v155
	v_cvt_pk_bf16_f32 v15, v156, v157
	v_cvt_pk_bf16_f32 v17, v16, v17
	v_cvt_pk_bf16_f32 v16, v236, v237
	s_nop 1
	v_mfma_f32_16x16x32_bf16 v[2:5], v[54:57], v[14:17], v[2:5]
	v_mfma_f32_16x16x32_bf16 v[102:105], v[118:121], v[14:17], v[102:105]
	v_mfma_f32_16x16x32_bf16 v[98:101], v[114:117], v[14:17], v[98:101]
	v_mfma_f32_16x16x32_bf16 v[94:97], v[138:141], v[14:17], v[94:97]
	v_mfma_f32_16x16x32_bf16 v[90:93], v[158:161], v[14:17], v[90:93]
	s_bitcmp1_b32 s41, 8
	s_cbranch_scc0 .LBB0_714
